# FFN-down epilogue: seven of the eight gain/bias quads requested at the start of the epilogue behind the first statistics loads
# speedup vs baseline: 1.0059x; 1.0059x over previous
; DI float bperm(float v, int srclane) { return __int_as_float(__builtin_amdgcn_ds_bpermute(srclane << 2, __float_as_int(v))); }
; DI u32x4 pack8(const float (&v)[8]) { u32x4 w; w.x = pk2(v[0], v[1]); w.y = pk2(v[2], v[3]); w.z = pk2(v[4], v[5]); w.w = pk2(v[6], v[7]); return w; }
; DI void row_stats(const float* STAT, int row, int fq, int lane, float& mu, float& rstd) {
;     const f32x4 a = *(const f32x4*)(STAT + (size_t)row * 32 + fq * 8), b = *(const f32x4*)(STAT + (size_t)row * 32 + fq * 8 + 4);
;     float s = (a[0] + a[2]) + (b[0] + b[2]), q = (a[1] + a[3]) + (b[1] + b[3]);
;     s += bperm(s, lane ^ 16); q += bperm(q, lane ^ 16); s += bperm(s, lane ^ 32); q += bperm(q, lane ^ 32);
;     mu = s * (1.0f / 1024.0f); rstd = __builtin_amdgcn_rsqf(fmaxf(q * (1.0f / 1024.0f) - mu * mu, 0.f) + EPS);
;     DI void operator()(const f32x4 (&acc)[2][2][4][2], const pg8::Unit& u, int wr, int wc, int fr, int fq) const {
;         asm volatile("" : "+v"(fr), "+v"(fq));
;         const int row0 = u.pm * 256 + wr * 64 + fr, col0 = u.pn * 256 + wc * 32 + 8 * fq, lane = fq * 16 + fr;
; #pragma unroll
;         for (int ai = 0; ai < 2; ++ai)
; #pragma unroll
;             for (int m = 0; m < 4; ++m) { const int row = row0 + ai * 128 + m * 16; const size_t off = (size_t)row * DMODEL + col0; float mu, rstd; row_stats(STAT, row, fq, lane, mu, rstd);
; #pragma unroll
;                 for (int bj = 0; bj < 2; ++bj) { float p[8]; unpack8(*(const u32x4*)(XBin + off + bj * 128), p);
;                     const f32x4 g0 = *(const f32x4*)(g + col0 + bj * 128), g1 = *(const f32x4*)(g + col0 + bj * 128 + 4), b0 = *(const f32x4*)(b + col0 + bj * 128), b1 = *(const f32x4*)(b + col0 + bj * 128 + 4);
;                     float o[8];
; #pragma unroll
;                     for (int k = 0; k < 8; ++k) { const float gg = k < 4 ? g0[k & 3] : g1[k & 3], bb = k < 4 ? b0[k & 3] : b1[k & 3]; const float x1 = (p[k] - mu) * rstd * gg + bb; o[k] = x1 * ALPHA + acc[ai][bj][m][k >> 2][k & 3]; }
;                     if (out32) { *(f32x4*)(out32 + off + bj * 128) = (f32x4){o[0], o[1], o[2], o[3]}; *(f32x4*)(out32 + off + bj * 128 + 4) = (f32x4){o[4], o[5], o[6], o[7]}; }
;                     else *(u32x4*)(XBout + off + bj * 128) = pack8(o); }
.LBB0_1979:
	s_lshl_b32 s2, s95, 8
	v_mov_b32_e32 v140, v159
	v_mov_b32_e32 v141, v158
	s_add_i32 s2, s2, s58
	s_andn2_b64 vcc, exec, s[44:45]
	v_add_u32_e32 v146, s2, v141
	s_lshl_b32 s2, s15, 8
	s_or_b32 s2, s2, s82
	v_lshlrev_b32_e32 v144, 3, v140
	v_lshlrev_b32_e32 v141, 2, v141
	v_add_u32_e32 v148, s2, v144
	v_lshl_add_u32 v140, v140, 6, v141
	v_ashrrev_i32_e32 v147, 31, v146
	v_ashrrev_i32_e32 v149, 31, v148
	v_xor_b32_e32 v163, 64, v140
	v_xor_b32_e32 v162, 0x80, v140
	v_lshlrev_b64 v[140:141], 10, v[146:147]
	v_lshl_add_u64 v[156:157], v[140:141], 0, v[148:149]
	v_lshlrev_b64 v[140:141], 7, v[146:147]
	v_ashrrev_i32_e32 v145, 31, v144
	v_lshl_add_u64 v[140:141], s[36:37], 0, v[140:141]
	v_lshl_add_u64 v[150:151], v[144:145], 2, v[140:141]
	global_load_dwordx4 v[140:143], v[150:151], off offset:16
	s_nop 0
	global_load_dwordx4 v[150:153], v[150:151], off
	v_lshlrev_b64 v[184:185], 2, v[148:149]
	v_lshl_add_u64 v[182:183], s[20:21], 0, v[184:185]
	v_lshl_add_u64 v[184:185], s[22:23], 0, v[184:185]
	global_load_dwordx4 v[220:223], v[182:183], off offset:16
	global_load_dwordx4 v[224:227], v[182:183], off
	global_load_dwordx4 v[228:231], v[184:185], off offset:16
	global_load_dwordx4 v[232:235], v[184:185], off
	global_load_dwordx4 v[242:245], v[182:183], off offset:528
	global_load_dwordx4 v[246:249], v[182:183], off offset:512
	global_load_dwordx4 v[250:253], v[184:185], off offset:528
	s_mov_b32 s2, 0x3a800000
	v_cndmask_b32_e64 v147, 0, 1, s[44:45]
	v_cmp_ne_u32_e64 s[18:19], 1, v147
	s_waitcnt vmcnt(7)
	v_pk_add_f32 v[140:141], v[140:141], v[142:143]
	v_pk_add_f32 v[150:151], v[150:151], v[152:153]
	s_nop 0
	v_pk_add_f32 v[140:141], v[150:151], v[140:141]
	ds_bpermute_b32 v142, v163, v140
	ds_bpermute_b32 v143, v163, v141
	v_lshl_add_u64 v[150:151], v[156:157], 1, s[26:27]
	global_load_dwordx4 v[164:167], v[150:151], off
	v_lshl_add_u64 v[156:157], v[156:157], 2, s[28:29]
	s_waitcnt lgkmcnt(0)
	v_pk_add_f32 v[140:141], v[140:141], v[142:143]
	ds_bpermute_b32 v142, v162, v140
	ds_bpermute_b32 v143, v162, v141
	s_waitcnt lgkmcnt(0)
	v_pk_add_f32 v[140:141], v[140:141], v[142:143]
	s_nop 0
	v_pk_mul_f32 v[152:153], v[140:141], s[2:3] op_sel_hi:[1,0]
	s_waitcnt vmcnt(0)
	v_lshlrev_b32_e32 v184, 16, v164
	v_fma_f32 v140, -v152, v152, v153
	v_max_f32_e32 v140, 0, v140
	v_add_f32_e32 v140, 0x3727c5ac, v140
	v_rsq_f32_e32 v154, v140
	v_lshlrev_b64 v[140:141], 2, v[148:149]
	v_lshl_add_u64 v[142:143], s[20:21], 0, v[140:141]
	v_lshl_add_u64 v[140:141], s[22:23], 0, v[140:141]
	s_nop 1
	v_mov_b32_e32 v168, v220
	v_mov_b32_e32 v169, v221
	v_mov_b32_e32 v170, v222
	v_mov_b32_e32 v171, v223
	v_mov_b32_e32 v172, v224
	v_mov_b32_e32 v173, v225
	v_mov_b32_e32 v174, v226
	v_mov_b32_e32 v175, v227
	v_mov_b32_e32 v176, v228
	v_mov_b32_e32 v177, v229
	v_mov_b32_e32 v178, v230
	v_mov_b32_e32 v179, v231
	v_mov_b32_e32 v180, v232
	v_mov_b32_e32 v181, v233
	v_mov_b32_e32 v182, v234
	v_mov_b32_e32 v183, v235
	v_and_b32_e32 v185, 0xffff0000, v164
	v_lshlrev_b32_e32 v164, 16, v165
	v_and_b32_e32 v165, 0xffff0000, v165
	v_pk_add_f32 v[164:165], v[164:165], v[152:153] op_sel_hi:[1,0] neg_lo:[0,1] neg_hi:[0,1]
	v_pk_add_f32 v[184:185], v[184:185], v[152:153] op_sel_hi:[1,0] neg_lo:[0,1] neg_hi:[0,1]
	v_pk_mul_f32 v[164:165], v[164:165], v[154:155] op_sel_hi:[1,0]
	v_pk_mul_f32 v[184:185], v[184:185], v[154:155] op_sel_hi:[1,0]
	s_waitcnt vmcnt(0)
	v_pk_fma_f32 v[164:165], v[174:175], v[164:165], v[182:183]
	s_nop 0
	v_pk_fma_f32 v[128:129], v[164:165], s[86:87], v[128:129] op_sel_hi:[1,0,1]
	v_lshlrev_b32_e32 v164, 16, v166
	v_and_b32_e32 v165, 0xffff0000, v166
	v_pk_add_f32 v[164:165], v[164:165], v[152:153] op_sel_hi:[1,0] neg_lo:[0,1] neg_hi:[0,1]
	v_pk_fma_f32 v[172:173], v[172:173], v[184:185], v[180:181]
	v_pk_mul_f32 v[164:165], v[164:165], v[154:155] op_sel_hi:[1,0]
	v_pk_fma_f32 v[126:127], v[172:173], s[86:87], v[126:127] op_sel_hi:[1,0,1]
	v_pk_fma_f32 v[164:165], v[168:169], v[164:165], v[176:177]
	s_nop 0
	v_pk_fma_f32 v[122:123], v[164:165], s[86:87], v[122:123] op_sel_hi:[1,0,1]
	v_lshlrev_b32_e32 v164, 16, v167
	v_and_b32_e32 v165, 0xffff0000, v167
	v_pk_add_f32 v[164:165], v[164:165], v[152:153] op_sel_hi:[1,0] neg_lo:[0,1] neg_hi:[0,1]
	s_nop 0
	v_pk_mul_f32 v[164:165], v[164:165], v[154:155] op_sel_hi:[1,0]
	s_nop 0
	v_pk_fma_f32 v[164:165], v[170:171], v[164:165], v[178:179]
	s_nop 0
	v_pk_fma_f32 v[124:125], v[164:165], s[86:87], v[124:125] op_sel_hi:[1,0,1]
	s_cbranch_vccnz .LBB0_1981
	s_mov_b64 s[2:3], 0
	global_store_dwordx4 v[156:157], v[126:129], off
	global_store_dwordx4 v[156:157], v[122:125], off offset:16
	s_branch .LBB0_1982

; DI u32x4 pack8(const float (&v)[8]) { u32x4 w; w.x = pk2(v[0], v[1]); w.y = pk2(v[2], v[3]); w.z = pk2(v[4], v[5]); w.w = pk2(v[6], v[7]); return w; }
;     DI void operator()(const f32x4 (&acc)[2][2][4][2], const pg8::Unit& u, int wr, int wc, int fr, int fq) const {
;     ...
;                 for (int bj = 0; bj < 2; ++bj) { float p[8]; unpack8(*(const u32x4*)(XBin + off + bj * 128), p);
;                     const f32x4 g0 = *(const f32x4*)(g + col0 + bj * 128), g1 = *(const f32x4*)(g + col0 + bj * 128 + 4), b0 = *(const f32x4*)(b + col0 + bj * 128), b1 = *(const f32x4*)(b + col0 + bj * 128 + 4);
;                     float o[8];
; #pragma unroll
;                     for (int k = 0; k < 8; ++k) { const float gg = k < 4 ? g0[k & 3] : g1[k & 3], bb = k < 4 ? b0[k & 3] : b1[k & 3]; const float x1 = (p[k] - mu) * rstd * gg + bb; o[k] = x1 * ALPHA + acc[ai][bj][m][k >> 2][k & 3]; }
;                     if (out32) { *(f32x4*)(out32 + off + bj * 128) = (f32x4){o[0], o[1], o[2], o[3]}; *(f32x4*)(out32 + off + bj * 128 + 4) = (f32x4){o[4], o[5], o[6], o[7]}; }
;                     else *(u32x4*)(XBout + off + bj * 128) = pack8(o); }
.LBB0_1984:
	global_load_dwordx4 v[122:125], v[150:151], off offset:256
	s_nop 0
	s_nop 1
	v_mov_b32_e32 v126, v242
	v_mov_b32_e32 v127, v243
	v_mov_b32_e32 v128, v244
	v_mov_b32_e32 v129, v245
	v_mov_b32_e32 v164, v246
	v_mov_b32_e32 v165, v247
	v_mov_b32_e32 v166, v248
	v_mov_b32_e32 v167, v249
	v_mov_b32_e32 v168, v250
	v_mov_b32_e32 v169, v251
	v_mov_b32_e32 v170, v252
	v_mov_b32_e32 v171, v253
	global_load_dwordx4 v[172:175], v[140:141], off offset:512
	v_mov_b32_e32 v153, v152
	v_mov_b32_e32 v155, v154
	s_and_b64 vcc, exec, s[18:19]
	s_waitcnt vmcnt(1)
	v_lshlrev_b32_e32 v176, 16, v122
	v_and_b32_e32 v177, 0xffff0000, v122
	v_lshlrev_b32_e32 v122, 16, v123
	v_and_b32_e32 v123, 0xffff0000, v123
	v_pk_add_f32 v[122:123], v[122:123], v[152:153] neg_lo:[0,1] neg_hi:[0,1]
	v_pk_add_f32 v[176:177], v[176:177], v[152:153] neg_lo:[0,1] neg_hi:[0,1]
	v_pk_mul_f32 v[122:123], v[154:155], v[122:123]
	v_pk_mul_f32 v[176:177], v[154:155], v[176:177]
	s_waitcnt vmcnt(0)
	v_mov_b32_e32 v186, v172
	v_mov_b32_e32 v187, v173
	v_mov_b32_e32 v196, v174
	v_mov_b32_e32 v197, v175
	v_pk_fma_f32 v[122:123], v[166:167], v[122:123], v[174:175]
	v_pk_fma_f32 v[164:165], v[164:165], v[176:177], v[172:173]
	v_pk_fma_f32 v[120:121], v[122:123], s[86:87], v[120:121] op_sel_hi:[1,0,1]
	v_lshlrev_b32_e32 v122, 16, v124
	v_and_b32_e32 v123, 0xffff0000, v124
	v_pk_add_f32 v[122:123], v[122:123], v[152:153] neg_lo:[0,1] neg_hi:[0,1]
	v_pk_fma_f32 v[118:119], v[164:165], s[86:87], v[118:119] op_sel_hi:[1,0,1]
	v_pk_mul_f32 v[122:123], v[154:155], v[122:123]
	s_nop 0
	v_pk_fma_f32 v[122:123], v[126:127], v[122:123], v[168:169]
	s_nop 0
	v_pk_fma_f32 v[114:115], v[122:123], s[86:87], v[114:115] op_sel_hi:[1,0,1]
	v_lshlrev_b32_e32 v122, 16, v125
	v_and_b32_e32 v123, 0xffff0000, v125
	v_pk_add_f32 v[122:123], v[122:123], v[152:153] neg_lo:[0,1] neg_hi:[0,1]
	s_nop 0
	v_pk_mul_f32 v[122:123], v[154:155], v[122:123]
	s_nop 0
	v_pk_fma_f32 v[122:123], v[128:129], v[122:123], v[170:171]
	s_nop 0
	v_pk_fma_f32 v[116:117], v[122:123], s[86:87], v[116:117] op_sel_hi:[1,0,1]
	s_cbranch_vccnz .LBB0_2032
	global_store_dwordx4 v[156:157], v[118:121], off offset:512
	global_store_dwordx4 v[156:157], v[114:117], off offset:528
	s_cbranch_execnz .LBB0_1987
